# post-phase causal gating: LDS B-fragment reads software-pipelined one block ahead into fresh VGPRs (double-buffered), mid-block lgkmcnt(0) waits removed; on top of v33
# baseline (speedup 1.0000x reference)
; #define LAS __attribute__((address_space(3)))
; __device__ __forceinline__ unsigned pk2(float lo, float hi) { unsigned r; asm volatile("v_cvt_pk_bf16_f32 %0, %1, %2" : "=v"(r) : "v"(lo), "v"(hi)); return r; }
; __device__ __forceinline__ void post_phase(const Args& a, int li, LAS unsigned char* lds) {
;     ...
;             { const int cp = tid & 63, tp = tid >> 6; const int c0 = 128 * g + 2 * cp; const float g0 = bn_g[c0], g1 = bn_g[c0 + 1], b0 = bn_b[c0], b1 = bn_b[c0 + 1];
;               unsigned wa_[8], wb_[8];
; #pragma unroll
;               for (int it = 0; it < 8; ++it) { const int tt = tp + 8 * it; wa_[it] = *(const unsigned*)(proj + (t0 + 2 * tt) * P_EVEN + 2304 + c0); wb_[it] = *(const unsigned*)(proj + (t0 + 2 * tt + 1) * P_EVEN + 2304 + c0); }
; #pragma unroll
;               for (int it = 0; it < 8; ++it) { const int tt = tp + 8 * it; const unsigned wa = wa_[it], wb = wb_[it];
;                   const f32x2 sa = *(const LAS f32x2*)(lds + PZ_STAT + (2 * tt) * 8), sb = *(const LAS f32x2*)(lds + PZ_STAT + (2 * tt + 1) * 8);
;                   const float za0 = (bflo(wa) - sa.x) * sa.y * g0 + b0, za1 = (bfhi(wa) - sa.x) * sa.y * g1 + b1, zb0 = (bflo(wb) - sb.x) * sb.y * g0 + b0, zb1 = (bfhi(wb) - sb.x) * sb.y * g1 + b1;
;                   *(LAS unsigned*)(lds + PZ_ZT + (2 * cp) * 272 + (2 * tt) * 2) = pk2(za0, zb0); *(LAS unsigned*)(lds + PZ_ZT + (2 * cp + 1) * 272 + (2 * tt) * 2) = pk2(za1, zb1); } }
.LBB0_655:
	v_lshl_add_u64 v[4:5], s[24:25], 0, v[16:17]
	v_add_co_u32_e32 v6, vcc, 0xe001000, v4
	v_lshl_add_u64 v[0:1], v[124:125], 0, s[26:27]
	s_nop 0
	v_addc_co_u32_e32 v7, vcc, 0, v5, vcc
	flat_load_dword v8, v[6:7] offset:512
	v_add_co_u32_e32 v6, vcc, 0xe002000, v4
	v_lshl_add_u64 v[2:3], v[126:127], 0, s[26:27]
	s_nop 0
	v_addc_co_u32_e32 v7, vcc, 0, v5, vcc
	flat_load_dword v9, v[6:7] offset:2048
	v_add_co_u32_e32 v6, vcc, 0xe017000, v4
	global_load_dwordx2 v[0:1], v[0:1], off
	s_nop 0
	v_addc_co_u32_e32 v7, vcc, 0, v5, vcc
	global_load_dwordx2 v[2:3], v[2:3], off
	s_mov_b32 s2, 0x5b00000
	flat_load_dword v10, v[6:7] offset:512
	v_add_co_u32_e32 v6, vcc, 0xe018000, v4
	v_add_u32_e32 v69, v87, v93
	s_nop 0
	v_addc_co_u32_e32 v7, vcc, 0, v5, vcc
	flat_load_dword v11, v[6:7] offset:2048
	v_add_co_u32_e32 v6, vcc, 0xe02d000, v4
	v_lshl_add_u64 v[16:17], v[16:17], 0, s[12:13]
	s_nop 0
	v_addc_co_u32_e32 v7, vcc, 0, v5, vcc
	flat_load_dword v12, v[6:7] offset:512
	v_add_co_u32_e32 v6, vcc, 0xe02e000, v4
	s_nop 1
	v_addc_co_u32_e32 v7, vcc, 0, v5, vcc
	flat_load_dword v13, v[6:7] offset:2048
	v_add_co_u32_e32 v6, vcc, 0xe043000, v4
	s_nop 1
	v_addc_co_u32_e32 v7, vcc, 0, v5, vcc
	flat_load_dword v14, v[6:7] offset:512
	v_add_co_u32_e32 v6, vcc, 0xe044000, v4
	s_nop 1
	v_addc_co_u32_e32 v7, vcc, 0, v5, vcc
	flat_load_dword v15, v[6:7] offset:2048
	v_add_co_u32_e32 v6, vcc, 0xe059000, v4
	s_nop 1
	v_addc_co_u32_e32 v7, vcc, 0, v5, vcc
	flat_load_dword v37, v[6:7] offset:512
	v_add_co_u32_e32 v6, vcc, 0xe05a000, v4
	s_nop 1
	v_addc_co_u32_e32 v7, vcc, 0, v5, vcc
	flat_load_dword v40, v[6:7] offset:2048
	v_add_co_u32_e32 v6, vcc, 0xe06f000, v4
	s_nop 1
	v_addc_co_u32_e32 v7, vcc, 0, v5, vcc
	flat_load_dword v41, v[6:7] offset:512
	v_add_co_u32_e32 v6, vcc, 0xe070000, v4
	s_nop 1
	v_addc_co_u32_e32 v7, vcc, 0, v5, vcc
	flat_load_dword v42, v[6:7] offset:2048
	v_add_co_u32_e32 v6, vcc, 0xe085000, v4
	s_nop 1
	v_addc_co_u32_e32 v7, vcc, 0, v5, vcc
	flat_load_dword v43, v[6:7] offset:512
	v_add_co_u32_e32 v6, vcc, 0xe086000, v4
	s_nop 1
	v_addc_co_u32_e32 v7, vcc, 0, v5, vcc
	flat_load_dword v44, v[6:7] offset:2048
	v_add_co_u32_e32 v6, vcc, 0xe09b000, v4
	s_nop 1
	v_addc_co_u32_e32 v7, vcc, 0, v5, vcc
	v_add_co_u32_e32 v4, vcc, 0xe09c000, v4
	flat_load_dword v45, v[6:7] offset:512
	s_nop 0
	v_addc_co_u32_e32 v5, vcc, 0, v5, vcc
	flat_load_dword v46, v[4:5] offset:2048
	s_waitcnt vmcnt(0) lgkmcnt(0)
	v_lshlrev_b32_e32 v47, 16, v8
	v_and_b32_e32 v8, 0xffff0000, v8
	ds_read_b128 v[4:7], v99
	s_waitcnt lgkmcnt(0)
	v_sub_f32_e32 v47, v47, v4
	v_sub_f32_e32 v4, v8, v4
	v_mul_f32_e32 v47, v5, v47
	v_mul_f32_e32 v4, v5, v4
	v_lshlrev_b32_e32 v5, 16, v9
	v_sub_f32_e32 v5, v5, v6
	v_and_b32_e32 v8, 0xffff0000, v9
	v_mul_f32_e32 v5, v7, v5
	v_sub_f32_e32 v6, v8, v6
	v_fma_f32 v4, v1, v4, v3
	v_fma_f32 v5, v0, v5, v2
	v_mul_f32_e32 v6, v7, v6
	v_fma_f32 v47, v0, v47, v2
	v_fma_f32 v6, v1, v6, v3
	v_cvt_pk_bf16_f32 v5, v47, v5
	ds_write_b32 v214, v5 offset:1024
	v_cvt_pk_bf16_f32 v4, v4, v6
	ds_write_b32 v214, v4 offset:1296
	ds_read_b128 v[4:7], v215
	v_lshlrev_b32_e32 v8, 16, v10
	v_and_b32_e32 v9, 0xffff0000, v10
	s_waitcnt lgkmcnt(0)
	v_sub_f32_e32 v8, v8, v4
	v_sub_f32_e32 v4, v9, v4
	v_mul_f32_e32 v8, v5, v8
	v_mul_f32_e32 v4, v5, v4
	v_lshlrev_b32_e32 v5, 16, v11
	v_sub_f32_e32 v5, v5, v6
	v_and_b32_e32 v9, 0xffff0000, v11
	v_mul_f32_e32 v5, v7, v5
	v_sub_f32_e32 v6, v9, v6
	v_fma_f32 v4, v1, v4, v3
	v_fma_f32 v5, v0, v5, v2
	v_mul_f32_e32 v6, v7, v6
	v_fma_f32 v8, v0, v8, v2
	v_fma_f32 v6, v1, v6, v3
	v_cvt_pk_bf16_f32 v5, v8, v5
	ds_write_b32 v216, v5 offset:1024
	v_cvt_pk_bf16_f32 v4, v4, v6
	ds_write_b32 v216, v4 offset:1296
	ds_read_b128 v[4:7], v217
	v_lshlrev_b32_e32 v8, 16, v12
	v_and_b32_e32 v9, 0xffff0000, v12
	s_waitcnt lgkmcnt(0)
	v_sub_f32_e32 v8, v8, v4
	v_sub_f32_e32 v4, v9, v4
	v_mul_f32_e32 v8, v5, v8
	v_mul_f32_e32 v4, v5, v4
	s_waitcnt vmcnt(0)
	v_lshlrev_b32_e32 v5, 16, v13
	v_sub_f32_e32 v5, v5, v6
	v_and_b32_e32 v9, 0xffff0000, v13
	v_mul_f32_e32 v5, v7, v5
	v_sub_f32_e32 v6, v9, v6
	v_fma_f32 v4, v1, v4, v3
	v_fma_f32 v5, v0, v5, v2
	v_mul_f32_e32 v6, v7, v6
	v_fma_f32 v8, v0, v8, v2
	v_fma_f32 v6, v1, v6, v3
	v_cvt_pk_bf16_f32 v5, v8, v5
	ds_write_b32 v218, v5 offset:1024
	v_cvt_pk_bf16_f32 v4, v4, v6
	ds_write_b32 v218, v4 offset:1296
	ds_read_b128 v[4:7], v219
	v_lshlrev_b32_e32 v8, 16, v14
	v_and_b32_e32 v9, 0xffff0000, v14
	s_waitcnt lgkmcnt(0)
	v_sub_f32_e32 v8, v8, v4
	v_sub_f32_e32 v4, v9, v4
	v_mul_f32_e32 v8, v5, v8
	v_mul_f32_e32 v4, v5, v4
	v_lshlrev_b32_e32 v5, 16, v15
	v_sub_f32_e32 v5, v5, v6
	v_and_b32_e32 v9, 0xffff0000, v15
	v_mul_f32_e32 v5, v7, v5
	v_sub_f32_e32 v6, v9, v6
	v_fma_f32 v4, v1, v4, v3
	v_fma_f32 v5, v0, v5, v2
	v_mul_f32_e32 v6, v7, v6
	v_fma_f32 v8, v0, v8, v2
	v_fma_f32 v6, v1, v6, v3
	v_cvt_pk_bf16_f32 v5, v8, v5
	ds_write_b32 v220, v5 offset:1024
	v_cvt_pk_bf16_f32 v4, v4, v6
	ds_write_b32 v220, v4 offset:1296
	ds_read_b128 v[4:7], v221
	v_lshlrev_b32_e32 v8, 16, v37
	v_and_b32_e32 v9, 0xffff0000, v37
	v_ashrrev_i32_e32 v37, 31, v36
	s_waitcnt lgkmcnt(0)
	v_sub_f32_e32 v8, v8, v4
	v_sub_f32_e32 v4, v9, v4
	v_mul_f32_e32 v8, v5, v8
	v_mul_f32_e32 v4, v5, v4
	v_lshlrev_b32_e32 v5, 16, v40
	v_sub_f32_e32 v5, v5, v6
	v_and_b32_e32 v9, 0xffff0000, v40
	v_mul_f32_e32 v5, v7, v5
	v_sub_f32_e32 v6, v9, v6
	v_fma_f32 v4, v1, v4, v3
	v_fma_f32 v5, v0, v5, v2
	v_mul_f32_e32 v6, v7, v6
	v_fma_f32 v8, v0, v8, v2
	v_fma_f32 v6, v1, v6, v3
	v_cvt_pk_bf16_f32 v5, v8, v5
	ds_write_b32 v222, v5 offset:1024
	v_cvt_pk_bf16_f32 v4, v4, v6
	ds_write_b32 v222, v4 offset:1296
	ds_read_b128 v[4:7], v223
	v_lshlrev_b32_e32 v8, 16, v41
	v_and_b32_e32 v9, 0xffff0000, v41
	v_lshl_add_u64 v[40:41], s[24:25], 0, v[18:19]
	v_lshl_add_u64 v[18:19], v[18:19], 0, s[12:13]
	s_waitcnt lgkmcnt(0)
; #define LAS __attribute__((address_space(3)))
; __device__ __forceinline__ void post_phase(const Args& a, int li, LAS unsigned char* lds) {
;     ...
;               for (int it = 0; it < 8; ++it) { const int tt = tp + 8 * it; const unsigned wa = wa_[it], wb = wb_[it];
;                   const f32x2 sa = *(const LAS f32x2*)(lds + PZ_STAT + (2 * tt) * 8), sb = *(const LAS f32x2*)(lds + PZ_STAT + (2 * tt + 1) * 8);
;                   const float za0 = (bflo(wa) - sa.x) * sa.y * g0 + b0, za1 = (bfhi(wa) - sa.x) * sa.y * g1 + b1, zb0 = (bflo(wb) - sb.x) * sb.y * g0 + b0, zb1 = (bfhi(wb) - sb.x) * sb.y * g1 + b1;
;                   *(LAS unsigned*)(lds + PZ_ZT + (2 * cp) * 272 + (2 * tt) * 2) = pk2(za0, zb0); *(LAS unsigned*)(lds + PZ_ZT + (2 * cp + 1) * 272 + (2 * tt) * 2) = pk2(za1, zb1); } }
;             { const int i = tid >> 2, seg = tid & 3; const bf16* src = spw + (size_t)(g * 128 + i) * 128 + 32 * seg;
; #pragma unroll
;               for (int v = 0; v < 4; ++v) *(LAS u32x4*)(lds + PZ_WM + i * 272 + (32 * seg + 8 * v) * 2) = *(const u32x4*)(src + 8 * v); }
;             __syncthreads();
;             { const int db = wave; bf16x8 Af[4];
; #pragma unroll
;               for (int kk = 0; kk < 4; ++kk) Af[kk] = *(const LAS bf16x8*)(lds + PZ_ZT + (16 * db + n16) * 272 + (32 * kk + 8 * q4) * 2);
;               u32x2 uws[8]; float biases[8];
; #pragma unroll
;               for (int ib = 0; ib < 8; ++ib) { const int i = 16 * ib + n16; uws[ib] = *(const u32x2*)(proj + (t0 + i) * P_EVEN + 1792 + 128 * g + 16 * db + 4 * q4); biases[ib] = sp_b[g * 128 + i]; }
; #pragma unroll
;               for (int ib = 0; ib < 8; ++ib) { f32x4 acc = {0.f, 0.f, 0.f, 0.f};
; #pragma unroll
;                   for (int kk = 0; kk < 4; ++kk) if (32 * kk <= 16 * ib + 15) { const bf16x8 Bf = *(const LAS bf16x8*)(lds + PZ_WM + (16 * ib + n16) * 272 + (32 * kk + 8 * q4) * 2);
;                       acc = __builtin_amdgcn_mfma_f32_16x16x32_bf16(Af[kk], Bf, acc, 0, 0, 0); }
;                   const int i = 16 * ib + n16, c = 128 * g + 16 * db + 4 * q4; const float bias = biases[ib];
;                   const u32x2 uw = uws[ib];
;                   u32x2 o; o.x = pk2(bflo(uw.x) * (acc[0] + bias), bfhi(uw.x) * (acc[1] + bias)); o.y = pk2(bflo(uw.y) * (acc[2] + bias), bfhi(uw.y) * (acc[3] + bias));
;                   *(u32x2*)(ycat + (t0 + i) * DM + 512 + c) = o; } }
	v_sub_f32_e32 v8, v8, v4
	v_sub_f32_e32 v4, v9, v4
	v_mul_f32_e32 v8, v5, v8
	v_mul_f32_e32 v4, v5, v4
	v_lshlrev_b32_e32 v5, 16, v42
	v_sub_f32_e32 v5, v5, v6
	v_and_b32_e32 v9, 0xffff0000, v42
	v_mul_f32_e32 v5, v7, v5
	v_sub_f32_e32 v6, v9, v6
	v_fma_f32 v4, v1, v4, v3
	v_fma_f32 v5, v0, v5, v2
	v_mul_f32_e32 v6, v7, v6
	v_fma_f32 v8, v0, v8, v2
	v_fma_f32 v6, v1, v6, v3
	v_cvt_pk_bf16_f32 v5, v8, v5
	ds_write_b32 v224, v5 offset:1024
	v_cvt_pk_bf16_f32 v4, v4, v6
	ds_write_b32 v224, v4 offset:1296
	ds_read_b128 v[4:7], v225
	v_lshlrev_b32_e32 v8, 16, v43
	v_and_b32_e32 v9, 0xffff0000, v43
	s_waitcnt lgkmcnt(0)
	v_sub_f32_e32 v8, v8, v4
	v_sub_f32_e32 v4, v9, v4
	v_mul_f32_e32 v8, v5, v8
	v_mul_f32_e32 v4, v5, v4
	v_lshlrev_b32_e32 v5, 16, v44
	v_sub_f32_e32 v5, v5, v6
	v_and_b32_e32 v9, 0xffff0000, v44
	v_mul_f32_e32 v5, v7, v5
	v_sub_f32_e32 v6, v9, v6
	v_fma_f32 v4, v1, v4, v3
	v_fma_f32 v5, v0, v5, v2
	v_mul_f32_e32 v6, v7, v6
	v_fma_f32 v8, v0, v8, v2
	v_fma_f32 v6, v1, v6, v3
	v_cvt_pk_bf16_f32 v5, v8, v5
	ds_write_b32 v234, v5 offset:1024
	v_cvt_pk_bf16_f32 v4, v4, v6
	ds_write_b32 v234, v4 offset:1296
	ds_read_b128 v[4:7], v235
	v_lshlrev_b32_e32 v8, 16, v45
	v_and_b32_e32 v9, 0xffff0000, v45
	v_lshl_add_u64 v[44:45], v[130:131], 0, s[26:27]
	s_add_u32 s26, s26, 0x200
	s_waitcnt lgkmcnt(0)
	v_sub_f32_e32 v8, v8, v4
	v_sub_f32_e32 v4, v9, v4
	v_mul_f32_e32 v8, v5, v8
	v_mul_f32_e32 v4, v5, v4
	v_lshlrev_b32_e32 v5, 16, v46
	v_sub_f32_e32 v5, v5, v6
	v_mul_f32_e32 v5, v7, v5
	v_fma_f32 v8, v0, v8, v2
	v_fma_f32 v0, v0, v5, v2
	v_and_b32_e32 v2, 0xffff0000, v46
	v_sub_f32_e32 v2, v2, v6
	v_mul_f32_e32 v2, v7, v2
	v_cvt_pk_bf16_f32 v0, v8, v0
	v_fma_f32 v4, v1, v4, v3
	v_fmac_f32_e32 v3, v1, v2
	ds_write_b32 v236, v0 offset:1024
	v_cvt_pk_bf16_f32 v0, v4, v3
	ds_write_b32 v236, v0 offset:1296
	v_lshl_add_u64 v[0:1], s[24:25], 0, v[38:39]
	v_add_co_u32_e32 v4, vcc, s2, v0
	s_mov_b32 s2, 0xe000000
	s_nop 0
	v_addc_co_u32_e32 v5, vcc, 0, v1, vcc
	flat_load_dwordx4 v[0:3], v[4:5]
	flat_load_dwordx4 v[8:11], v[4:5] offset:16
	flat_load_dwordx4 v[12:15], v[4:5] offset:32
	flat_load_dwordx4 v[52:55], v[4:5] offset:48
	v_add_co_u32_e32 v42, vcc, s2, v40
	s_mov_b32 s2, 0xe016000
	s_nop 0
	v_addc_co_u32_e32 v43, vcc, 0, v41, vcc
	s_addc_u32 s27, s27, 0
	v_lshl_add_u64 v[38:39], v[38:39], 0, s[28:29]
	s_cmpk_eq_i32 s26, 0x800
	s_waitcnt vmcnt(0) lgkmcnt(0)
	ds_write_b128 v237, v[0:3] offset:35840
	ds_write_b128 v237, v[8:11] offset:35856
	ds_write_b128 v237, v[12:15] offset:35872
	ds_write_b128 v237, v[52:55] offset:35888
	s_waitcnt lgkmcnt(0)
	s_barrier
	ds_read_b128 v[12:15], v238 offset:1024
	ds_read_b128 v[8:11], v238 offset:1088
	ds_read_b128 v[4:7], v238 offset:1152
	ds_read_b128 v[0:3], v238 offset:1216
	flat_load_dwordx2 v[48:49], v[42:43] offset:3584
	global_load_dword v60, v[44:45], off
	v_add_co_u32_e32 v42, vcc, s2, v40
	s_mov_b32 s2, 0xe02c000
	s_nop 0
	v_addc_co_u32_e32 v43, vcc, 0, v41, vcc
	flat_load_dwordx2 v[50:51], v[42:43] offset:3584
	global_load_dword v62, v[44:45], off offset:64
	v_add_co_u32_e32 v42, vcc, s2, v40
	s_mov_b32 s2, 0xe042000
	s_nop 0
	v_addc_co_u32_e32 v43, vcc, 0, v41, vcc
	flat_load_dwordx2 v[52:53], v[42:43] offset:3584
	global_load_dword v63, v[44:45], off offset:128
	v_add_co_u32_e32 v42, vcc, s2, v40
	s_mov_b32 s2, 0xe058000
	s_nop 0
	v_addc_co_u32_e32 v43, vcc, 0, v41, vcc
	flat_load_dwordx2 v[54:55], v[42:43] offset:3584
	global_load_dword v64, v[44:45], off offset:192
	v_add_co_u32_e32 v42, vcc, s2, v40
	s_mov_b32 s2, 0xe06e000
	s_nop 0
	v_addc_co_u32_e32 v43, vcc, 0, v41, vcc
	flat_load_dwordx2 v[56:57], v[42:43] offset:3584
	global_load_dword v65, v[44:45], off offset:256
	v_add_co_u32_e32 v42, vcc, s2, v40
	s_mov_b32 s2, 0xe084000
	s_nop 0
	v_addc_co_u32_e32 v43, vcc, 0, v41, vcc
	flat_load_dwordx2 v[58:59], v[42:43] offset:3584
	global_load_dword v66, v[44:45], off offset:320
	v_add_co_u32_e32 v42, vcc, s2, v40
	s_mov_b32 s2, 0xe09a000
	s_nop 0
	v_addc_co_u32_e32 v43, vcc, 0, v41, vcc
	v_add_co_u32_e32 v40, vcc, s2, v40
	flat_load_dwordx2 v[42:43], v[42:43] offset:3584
	s_nop 0
	global_load_dword v67, v[44:45], off offset:384
	v_addc_co_u32_e32 v41, vcc, 0, v41, vcc
	flat_load_dwordx2 v[40:41], v[40:41] offset:3584
	s_nop 0
	global_load_dword v68, v[44:45], off offset:448
	ds_read_b128 v[44:47], v69 offset:35840
	s_waitcnt lgkmcnt(0)
	v_mfma_f32_16x16x32_bf16 v[44:47], v[12:15], v[44:47], 0
	ds_read_b128 v[148:151], v69 offset:40192
	s_waitcnt vmcnt(0)
	v_lshlrev_b32_e32 v61, 16, v48
	s_nop 5
	v_add_f32_e32 v44, v60, v44
	v_and_b32_e32 v48, 0xffff0000, v48
	v_add_f32_e32 v45, v60, v45
	v_mul_f32_e32 v44, v44, v61
	v_mul_f32_e32 v45, v45, v48
	v_cvt_pk_bf16_f32 v44, v44, v45
	v_lshlrev_b32_e32 v45, 16, v49
	v_add_f32_e32 v46, v60, v46
	v_mul_f32_e32 v45, v46, v45
	v_and_b32_e32 v46, 0xffff0000, v49
	v_add_f32_e32 v47, v60, v47
	v_mul_f32_e32 v46, v47, v46
	v_lshlrev_b64 v[60:61], 1, v[36:37]
	v_cvt_pk_bf16_f32 v45, v45, v46
	v_lshl_add_u64 v[46:47], v[20:21], 0, v[60:61]
	flat_store_dwordx2 v[46:47], v[44:45] offset:1024
	s_waitcnt lgkmcnt(0)
	v_mfma_f32_16x16x32_bf16 v[44:47], v[12:15], v[148:151], 0
	ds_read_b128 v[188:191], v69 offset:44544
	ds_read_b128 v[192:195], v69 offset:44608
	v_lshlrev_b32_e32 v37, 16, v50
	v_add_u32_e32 v36, 0x80, v36
	s_nop 5
	v_add_f32_e32 v44, v62, v44
	v_mul_f32_e32 v37, v44, v37
	v_and_b32_e32 v44, 0xffff0000, v50
	v_add_f32_e32 v45, v62, v45
	v_mul_f32_e32 v44, v45, v44
	v_cvt_pk_bf16_f32 v44, v37, v44
	v_lshlrev_b32_e32 v37, 16, v51
	v_add_f32_e32 v45, v62, v46
	v_mul_f32_e32 v37, v45, v37
	v_and_b32_e32 v45, 0xffff0000, v51
	v_add_f32_e32 v46, v62, v47
	v_mul_f32_e32 v45, v46, v45
	v_lshl_add_u64 v[46:47], v[22:23], 0, v[60:61]
	v_cvt_pk_bf16_f32 v45, v37, v45
	flat_store_dwordx2 v[46:47], v[44:45] offset:1024
	s_waitcnt lgkmcnt(0)
; #define LAS __attribute__((address_space(3)))
; __device__ __forceinline__ unsigned pk2(float lo, float hi) { unsigned r; asm volatile("v_cvt_pk_bf16_f32 %0, %1, %2" : "=v"(r) : "v"(lo), "v"(hi)); return r; }
; __device__ __forceinline__ void post_phase(const Args& a, int li, LAS unsigned char* lds) {
;     ...
;               for (int ib = 0; ib < 8; ++ib) { f32x4 acc = {0.f, 0.f, 0.f, 0.f};
; #pragma unroll
;                   for (int kk = 0; kk < 4; ++kk) if (32 * kk <= 16 * ib + 15) { const bf16x8 Bf = *(const LAS bf16x8*)(lds + PZ_WM + (16 * ib + n16) * 272 + (32 * kk + 8 * q4) * 2);
;                       acc = __builtin_amdgcn_mfma_f32_16x16x32_bf16(Af[kk], Bf, acc, 0, 0, 0); }
;                   const int i = 16 * ib + n16, c = 128 * g + 16 * db + 4 * q4; const float bias = biases[ib];
;                   const u32x2 uw = uws[ib];
;                   u32x2 o; o.x = pk2(bflo(uw.x) * (acc[0] + bias), bfhi(uw.x) * (acc[1] + bias)); o.y = pk2(bflo(uw.y) * (acc[2] + bias), bfhi(uw.y) * (acc[3] + bias));
;                   *(u32x2*)(ycat + (t0 + i) * DM + 512 + c) = o; } }
;             __syncthreads();
;         }
;         { const int h = wave; bf16x8 Ag[4][4];
; #pragma unroll
;           for (int cb = 0; cb < 4; ++cb)
; #pragma unroll
;               for (int kk = 0; kk < 4; ++kk) Ag[cb][kk] = *(const bf16x8*)(gupt + (size_t)(64 * h + 16 * cb + n16) * 128 + 32 * kk + 8 * q4);
	v_mfma_f32_16x16x32_bf16 v[44:47], v[12:15], v[188:191], 0
	v_lshlrev_b32_e32 v37, 16, v52
	v_mfma_f32_16x16x32_bf16 v[44:47], v[8:11], v[192:195], v[44:47]
	ds_read_b128 v[148:151], v69 offset:48896
	ds_read_b128 v[152:155], v69 offset:48960
	s_nop 7
	v_add_f32_e32 v44, v63, v44
	v_mul_f32_e32 v37, v44, v37
	v_and_b32_e32 v44, 0xffff0000, v52
	v_add_f32_e32 v45, v63, v45
	v_mul_f32_e32 v44, v45, v44
	v_cvt_pk_bf16_f32 v44, v37, v44
	v_lshlrev_b32_e32 v37, 16, v53
	v_add_f32_e32 v45, v63, v46
	v_mul_f32_e32 v37, v45, v37
	v_and_b32_e32 v45, 0xffff0000, v53
	v_add_f32_e32 v46, v63, v47
	v_mul_f32_e32 v45, v46, v45
	v_lshl_add_u64 v[46:47], v[24:25], 0, v[60:61]
	v_cvt_pk_bf16_f32 v45, v37, v45
	flat_store_dwordx2 v[46:47], v[44:45] offset:1024
	s_waitcnt lgkmcnt(0)
	v_mfma_f32_16x16x32_bf16 v[44:47], v[12:15], v[148:151], 0
	v_lshlrev_b32_e32 v37, 16, v54
	v_mfma_f32_16x16x32_bf16 v[44:47], v[8:11], v[152:155], v[44:47]
	ds_read_b128 v[188:191], v69 offset:53248
	ds_read_b128 v[192:195], v69 offset:53312
	ds_read_b128 v[196:199], v69 offset:53376
	s_nop 7
	v_add_f32_e32 v44, v64, v44
	v_mul_f32_e32 v37, v44, v37
	v_and_b32_e32 v44, 0xffff0000, v54
	v_add_f32_e32 v45, v64, v45
	v_mul_f32_e32 v44, v45, v44
	v_cvt_pk_bf16_f32 v44, v37, v44
	v_lshlrev_b32_e32 v37, 16, v55
	v_add_f32_e32 v45, v64, v46
	v_mul_f32_e32 v37, v45, v37
	v_and_b32_e32 v45, 0xffff0000, v55
	v_add_f32_e32 v46, v64, v47
	v_mul_f32_e32 v45, v46, v45
	v_lshl_add_u64 v[46:47], v[26:27], 0, v[60:61]
	v_cvt_pk_bf16_f32 v45, v37, v45
	flat_store_dwordx2 v[46:47], v[44:45] offset:1024
	s_waitcnt lgkmcnt(0)
	v_mfma_f32_16x16x32_bf16 v[44:47], v[12:15], v[188:191], 0
	v_lshlrev_b32_e32 v37, 16, v56
	v_mfma_f32_16x16x32_bf16 v[44:47], v[8:11], v[192:195], v[44:47]
	v_mfma_f32_16x16x32_bf16 v[44:47], v[4:7], v[196:199], v[44:47]
	ds_read_b128 v[148:151], v69 offset:57600
	ds_read_b128 v[152:155], v69 offset:57664
	ds_read_b128 v[156:159], v69 offset:57728
	s_nop 7
	v_add_f32_e32 v44, v65, v44
	v_mul_f32_e32 v37, v44, v37
	v_and_b32_e32 v44, 0xffff0000, v56
	v_add_f32_e32 v45, v65, v45
	v_mul_f32_e32 v44, v45, v44
	v_cvt_pk_bf16_f32 v44, v37, v44
	v_lshlrev_b32_e32 v37, 16, v57
	v_add_f32_e32 v45, v65, v46
	v_mul_f32_e32 v37, v45, v37
	v_and_b32_e32 v45, 0xffff0000, v57
	v_add_f32_e32 v46, v65, v47
	v_mul_f32_e32 v45, v46, v45
	v_lshl_add_u64 v[46:47], v[28:29], 0, v[60:61]
	v_cvt_pk_bf16_f32 v45, v37, v45
	flat_store_dwordx2 v[46:47], v[44:45] offset:1024
	s_waitcnt lgkmcnt(0)
	v_mfma_f32_16x16x32_bf16 v[44:47], v[12:15], v[148:151], 0
	v_lshlrev_b32_e32 v37, 16, v58
	v_mfma_f32_16x16x32_bf16 v[44:47], v[8:11], v[152:155], v[44:47]
	v_mfma_f32_16x16x32_bf16 v[44:47], v[4:7], v[156:159], v[44:47]
	ds_read_b128 v[188:191], v69 offset:61952
	ds_read_b128 v[192:195], v69 offset:62016
	ds_read_b128 v[196:199], v69 offset:62080
	ds_read_b128 v[200:203], v69 offset:62144
	s_nop 7
	v_add_f32_e32 v44, v66, v44
	v_mul_f32_e32 v37, v44, v37
	v_and_b32_e32 v44, 0xffff0000, v58
	v_add_f32_e32 v45, v66, v45
	v_mul_f32_e32 v44, v45, v44
	v_cvt_pk_bf16_f32 v44, v37, v44
	v_lshlrev_b32_e32 v37, 16, v59
	v_add_f32_e32 v45, v66, v46
	v_mul_f32_e32 v37, v45, v37
	v_and_b32_e32 v45, 0xffff0000, v59
	v_add_f32_e32 v46, v66, v47
	v_mul_f32_e32 v45, v46, v45
	v_lshl_add_u64 v[46:47], v[30:31], 0, v[60:61]
	v_cvt_pk_bf16_f32 v45, v37, v45
	flat_store_dwordx2 v[46:47], v[44:45] offset:1024
	s_waitcnt lgkmcnt(0)
	v_mfma_f32_16x16x32_bf16 v[44:47], v[12:15], v[188:191], 0
	v_lshlrev_b32_e32 v37, 16, v42
	v_and_b32_e32 v42, 0xffff0000, v42
	v_mfma_f32_16x16x32_bf16 v[44:47], v[8:11], v[192:195], v[44:47]
	v_mfma_f32_16x16x32_bf16 v[44:47], v[4:7], v[196:199], v[44:47]
	v_mfma_f32_16x16x32_bf16 v[44:47], v[0:3], v[200:203], v[44:47]
	ds_read_b128 v[148:151], v239 offset:61952
	ds_read_b128 v[152:155], v239 offset:62016
	ds_read_b128 v[156:159], v239 offset:62080
	ds_read_b128 v[160:163], v239 offset:62144
	s_nop 7
	v_add_f32_e32 v44, v67, v44
	v_mul_f32_e32 v37, v44, v37
	v_add_f32_e32 v44, v67, v45
	v_mul_f32_e32 v42, v44, v42
	v_cvt_pk_bf16_f32 v42, v37, v42
	v_lshlrev_b32_e32 v37, 16, v43
	v_add_f32_e32 v44, v67, v46
	v_mul_f32_e32 v37, v44, v37
	v_and_b32_e32 v43, 0xffff0000, v43
	v_add_f32_e32 v44, v67, v47
	v_mul_f32_e32 v43, v44, v43
	v_lshl_add_u64 v[44:45], v[32:33], 0, v[60:61]
	v_cvt_pk_bf16_f32 v43, v37, v43
	flat_store_dwordx2 v[44:45], v[42:43] offset:1024
	s_waitcnt lgkmcnt(0)
	v_mfma_f32_16x16x32_bf16 v[12:15], v[12:15], v[148:151], 0
	s_nop 7
	s_nop 1
	v_mfma_f32_16x16x32_bf16 v[8:11], v[8:11], v[152:155], v[12:15]
	s_nop 4
	s_nop 7
	s_nop 1
	v_mfma_f32_16x16x32_bf16 v[4:7], v[4:7], v[156:159], v[8:11]
	s_nop 2
	s_nop 7
	s_nop 1
	v_mfma_f32_16x16x32_bf16 v[0:3], v[0:3], v[160:163], v[4:7]
	s_nop 2
	v_lshlrev_b32_e32 v4, 16, v40
	s_nop 3
	v_add_f32_e32 v0, v68, v0
	v_mul_f32_e32 v0, v0, v4
	v_and_b32_e32 v4, 0xffff0000, v40
	v_add_f32_e32 v1, v68, v1
	v_mul_f32_e32 v1, v1, v4
	v_cvt_pk_bf16_f32 v0, v0, v1
	v_lshlrev_b32_e32 v1, 16, v41
	v_add_f32_e32 v2, v68, v2
	v_mul_f32_e32 v1, v2, v1
	v_and_b32_e32 v2, 0xffff0000, v41
	v_add_f32_e32 v3, v68, v3
	v_mul_f32_e32 v2, v3, v2
	v_cvt_pk_bf16_f32 v1, v1, v2
	v_lshl_add_u64 v[2:3], v[34:35], 0, v[60:61]
	flat_store_dwordx2 v[2:3], v[0:1] offset:1024
	s_waitcnt lgkmcnt(0)
	s_barrier
	s_cbranch_scc0 .LBB0_655
	flat_load_dwordx4 v[0:3], v[100:101]
	flat_load_dwordx4 v[4:7], v[100:101] offset:64
	flat_load_dwordx4 v[8:11], v[100:101] offset:128
	flat_load_dwordx4 v[12:15], v[100:101] offset:192
	flat_load_dwordx4 v[16:19], v[102:103]
	flat_load_dwordx4 v[20:23], v[102:103] offset:64
	flat_load_dwordx4 v[24:27], v[102:103] offset:128
	flat_load_dwordx4 v[28:31], v[102:103] offset:192
	flat_load_dwordx4 v[32:35], v[104:105]
	flat_load_dwordx4 v[36:39], v[104:105] offset:64
	flat_load_dwordx4 v[40:43], v[104:105] offset:128
	flat_load_dwordx4 v[44:47], v[104:105] offset:192
	flat_load_dwordx4 v[48:51], v[106:107]
	flat_load_dwordx4 v[52:55], v[106:107] offset:64
	flat_load_dwordx4 v[56:59], v[106:107] offset:128
	flat_load_dwordx4 v[60:63], v[106:107] offset:192
	s_bfe_u32 s2, s7, 0x50007
	v_lshl_add_u64 v[150:151], v[136:137], 0, s[0:1]
	v_lshl_add_u64 v[152:153], v[138:139], 0, s[0:1]
	v_lshl_add_u64 v[154:155], v[140:141], 0, s[0:1]
	v_lshl_add_u64 v[156:157], v[142:143], 0, s[0:1]
	s_lshl_b64 s[0:1], s[46:47], 12
	s_mul_i32 s4, s2, 0x8800
	s_lshl_b64 s[2:3], s[46:47], 18
	v_lshl_add_u64 v[158:159], v[144:145], 0, s[0:1]
	s_lshl_b64 s[0:1], s[46:47], 17
	v_lshl_add_u64 v[148:149], v[134:135], 0, s[2:3]
	v_lshl_add_u64 v[160:161], v[146:147], 0, s[0:1]
	v_add_u32_e32 v241, s4, v93
	s_mov_b32 s2, 0
	s_branch .LBB0_658
